# static s_setprio 1 for waves 4-7 across the whole work-queue phase (retention, sample and prompt attention units) instead of only the prompt-attention loop
# speedup vs baseline: 1.0021x; 1.0021x over previous
; __device__ __forceinline__ int launder_tid() { int x = threadIdx.x; asm volatile("" : "+v"(x)); return x; }
; DI float wave_sum(float v) { v += shx(v, 32); v += shx(v, 16); v += shx(v, 8); v += shx(v, 4); v += shx(v, 2); v += shx(v, 1); return v; }
; DI void p2_units(const Params& p, LAS unsigned char* lds, int dup) {
;     const int tid = launder_tid(), lane = tid & 63;
;     float lam;
;     { float a = p.lam_q1[lane] * p.lam_k1[lane], c = p.lam_q2[lane] * p.lam_k2[lane]; a = wave_sum(a); c = wave_sum(c); lam = __expf(a) - __expf(c) + 0.2f; }
;     unsigned* ctr = (unsigned*)(p.ws + WS_CTL) + 128 * dup;
;     ...
;     for (;;) {
;         __syncthreads();
.LBB0_599:
	s_or_b64 exec, exec, s[0:1]
	v_readfirstlane_b32 s98, v182
	s_nop 0
	s_cmpk_lt_u32 s98, 0x100
	s_cbranch_scc1 .Lprio_p2
	s_setprio 1
.Lprio_p2:
	v_mov_b32_e32 v0, v182
	s_barrier
	v_mbcnt_hi_u32_b32 v6, -1, v155
	v_and_b32_e32 v1, 63, v0
	v_lshlrev_b32_e32 v1, 2, v1
	global_load_dword v2, v1, s[60:61]
	global_load_dword v3, v1, s[62:63]
	global_load_dword v4, v1, s[64:65]
	global_load_dword v5, v1, s[66:67]
	v_and_b32_e32 v8, 64, v6
	v_xor_b32_e32 v7, 32, v6
	v_add_u32_e32 v8, 64, v8
	v_xor_b32_e32 v9, 16, v6
	v_cmp_lt_i32_e32 vcc, v7, v8
	v_xor_b32_e32 v10, 8, v6
	v_xor_b32_e32 v11, 4, v6
	v_cndmask_b32_e32 v7, v6, v7, vcc
	v_cmp_lt_i32_e32 vcc, v9, v8
	v_xor_b32_e32 v12, 2, v6
	v_xor_b32_e32 v13, 1, v6
	v_cndmask_b32_e32 v9, v6, v9, vcc
	v_cmp_lt_i32_e32 vcc, v10, v8
	v_lshlrev_b32_e32 v185, 2, v7
	v_lshlrev_b32_e32 v186, 2, v9
	v_cndmask_b32_e32 v10, v6, v10, vcc
	v_cmp_lt_i32_e32 vcc, v11, v8
	v_lshlrev_b32_e32 v7, 2, v10
	s_add_u32 s54, s74, 0x16418400
	v_cndmask_b32_e32 v11, v6, v11, vcc
	v_cmp_lt_i32_e32 vcc, v12, v8
	s_addc_u32 s55, s75, 0
	s_add_u32 s56, s74, 0x1a558400
	v_cndmask_b32_e32 v12, v6, v12, vcc
	v_cmp_lt_i32_e32 vcc, v13, v8
	v_lshlrev_b32_e32 v8, 2, v11
	s_addc_u32 s57, s75, 0
	s_add_u32 s58, s74, 0x184b8400
	s_addc_u32 s59, s75, 0
	s_add_u32 s0, s74, 0x1e698400
	v_writelane_b32 v254, s0, 8
	s_addc_u32 s0, s75, 0
	v_writelane_b32 v254, s0, 9
	s_add_u32 s0, s72, 0x20b00000
	v_writelane_b32 v254, s0, 10
	s_addc_u32 s0, s73, 0
	s_add_u32 s93, s74, 0x1000
	v_writelane_b32 v254, s0, 11
	s_addc_u32 s0, s75, 0
	s_add_u32 s60, s74, 0x32c58400
	s_addc_u32 s61, s75, 0
	v_writelane_b32 v254, s0, 4
	s_add_u32 s0, s72, 0x20500000
	v_writelane_b32 v254, s0, 12
	s_addc_u32 s0, s73, 0
	v_writelane_b32 v254, s0, 13
	s_add_u32 s0, s74, 0xe198400
	v_lshlrev_b32_e32 v9, 2, v12
	v_writelane_b32 v254, s0, 14
	s_addc_u32 s0, s75, 0
	v_writelane_b32 v254, s0, 15
	s_add_u32 s0, s74, 0x122d8400
	v_writelane_b32 v254, s0, 16
	s_addc_u32 s0, s75, 0
	s_add_u32 s52, s74, 0xa058400
	s_addc_u32 s53, s75, 0
	v_cndmask_b32_e32 v6, v6, v13, vcc
	v_writelane_b32 v254, s0, 17
	s_add_u32 s0, s72, 0x20700000
	v_lshlrev_b32_e32 v6, 2, v6
	v_writelane_b32 v254, s0, 18
	s_addc_u32 s0, s73, 0
	v_writelane_b32 v254, s0, 19
	s_add_u32 s0, s72, 0x20900000
	v_writelane_b32 v254, s0, 20
	s_addc_u32 s0, s73, 0
	v_writelane_b32 v254, s0, 21
	s_add_u32 s0, s74, 0x12298400
	v_writelane_b32 v254, s0, 22
	s_addc_u32 s0, s75, 0
	v_writelane_b32 v254, s0, 23
	s_add_u32 s0, s74, 0x163d8400
	v_writelane_b32 v254, s0, 24
	s_addc_u32 s0, s75, 0
	s_add_u32 s33, s74, 0x2a858400
	s_addc_u32 s84, s75, 0
	v_writelane_b32 v254, s0, 25
	s_waitcnt vmcnt(2)
	v_mul_f32_e32 v10, v2, v3
	ds_bpermute_b32 v10, v185, v10
	s_waitcnt vmcnt(0)
	v_mul_f32_e32 v11, v4, v5
	ds_bpermute_b32 v11, v185, v11
	s_add_u32 s0, s44, 0x20000
	v_writelane_b32 v254, s0, 26
	s_waitcnt lgkmcnt(1)
	v_fmac_f32_e32 v10, v2, v3
	ds_bpermute_b32 v2, v186, v10
	s_waitcnt lgkmcnt(1)
	v_fmac_f32_e32 v11, v4, v5
	ds_bpermute_b32 v3, v186, v11
	s_addc_u32 s0, s45, 0
	v_writelane_b32 v254, s0, 27
	s_waitcnt lgkmcnt(1)
	v_add_f32_e32 v2, v10, v2
	ds_bpermute_b32 v4, v7, v2
	s_waitcnt lgkmcnt(1)
	v_add_f32_e32 v3, v11, v3
	ds_bpermute_b32 v5, v7, v3
	s_add_u32 s0, s46, 0x20000
	v_writelane_b32 v254, s0, 28
	s_waitcnt lgkmcnt(1)
	v_add_f32_e32 v2, v2, v4
	ds_bpermute_b32 v4, v8, v2
	s_waitcnt lgkmcnt(1)
	v_add_f32_e32 v3, v3, v5
	ds_bpermute_b32 v5, v8, v3
	s_addc_u32 s0, s47, 0
	s_add_i32 s96, 0, 0x27fc0
	s_waitcnt lgkmcnt(1)
	v_add_f32_e32 v2, v2, v4
	ds_bpermute_b32 v4, v9, v2
	s_waitcnt lgkmcnt(1)
	v_add_f32_e32 v3, v3, v5
	ds_bpermute_b32 v5, v9, v3
	v_mov_b32_e32 v1, 0
	s_mov_b32 s85, 0xc2fc0000
	s_waitcnt lgkmcnt(1)
	v_add_f32_e32 v2, v2, v4
	ds_bpermute_b32 v4, v6, v2
	s_waitcnt lgkmcnt(1)
	v_add_f32_e32 v3, v3, v5
	ds_bpermute_b32 v5, v6, v3
	s_mov_b32 s86, 0x800000
	s_movk_i32 s78, 0x1000
	s_waitcnt lgkmcnt(1)
	v_add_f32_e32 v2, v2, v4
	v_mul_f32_e32 v2, 0x3fb8aa3b, v2
	s_waitcnt lgkmcnt(0)
	v_add_f32_e32 v3, v3, v5
	v_mul_f32_e32 v3, 0x3fb8aa3b, v3
	v_exp_f32_e32 v2, v2
	v_exp_f32_e32 v3, v3
	s_movk_i32 s79, 0x2000
	s_movk_i32 s80, 0x3000
	s_movk_i32 s81, 0x100
	v_sub_f32_e32 v2, v2, v3
	s_movk_i32 s82, 0x90
	s_movk_i32 s83, 0x140
	v_mov_b32_e32 v187, 0x358637bd
	s_mov_b32 s97, 0x2a858000
	s_movk_i32 s87, 0x110
	s_mov_b32 s88, 0xcccccccd
	s_movk_i32 s89, 0xffec
	s_mov_b32 s90, 0x78787879
	s_movk_i32 s91, 0xffef
	v_writelane_b32 v254, s0, 29
	s_add_i32 s0, 0, 0x12800
	v_add_f32_e32 v188, 0x3e4ccccd, v2
	v_mov_b32_e32 v189, 1
	v_mov_b32_e32 v190, s96
	v_mov_b32_e32 v191, 0x42800000
	v_mov_b32_e32 v192, 0x42000000
	v_mov_b32_e32 v193, 4
	v_not_b32_e32 v194, 63
	v_mov_b32_e32 v195, 3
	s_mov_b32 s63, 0
	v_cmp_eq_u32_e64 s[4:5], 0, v0
	v_writelane_b32 v254, s0, 30
	s_and_b32 s98, s2, 7
	s_lshl_b32 s98, s98, 7
	s_addk_i32 s98, 0x1800
	s_add_u32 s100, s74, s98
	s_addc_u32 s101, s75, 0
	s_branch .LBB0_603

.LBB0_781:
	s_setprio 0
	v_readlane_b32 s68, v254, 6
	v_readlane_b32 s69, v254, 7
	v_readlane_b32 s66, v254, 2
	s_and_b64 vcc, exec, s[68:69]
	v_readlane_b32 s67, v254, 3
	s_cbranch_vccnz .LBB0_793
	v_or_b32_e32 v0, v184, v183
	s_movk_i32 s0, 0x3ff
	v_and_or_b32 v0, v0, s0, v182
	v_cmp_eq_u32_e32 vcc, 0, v0
	s_barrier
	s_and_saveexec_b64 s[0:1], vcc
	s_cbranch_execz .LBB0_792
	v_readlane_b32 s4, v254, 0
	v_readlane_b32 s5, v254, 1
	buffer_wbl2 sc1
	s_waitcnt vmcnt(0)
	s_load_dwordx2 s[4:5], s[4:5], 0x58
	v_mov_b32_e32 v2, 0
	s_mov_b64 s[6:7], exec
	v_mbcnt_lo_u32_b32 v1, s6, 0
	v_mbcnt_hi_u32_b32 v1, s7, v1
	s_waitcnt lgkmcnt(0)
	global_load_dword v0, v2, s[4:5] offset:40
	v_cmp_eq_u32_e32 vcc, 0, v1
	s_and_saveexec_b64 s[8:9], vcc
	s_cbranch_execz .LBB0_785
	s_bcnt1_i32_b64 s6, s[6:7]
	v_mov_b32_e32 v3, s6
	global_atomic_add v3, v2, v3, s[4:5] offset:32 sc0
